# w_out transpose split into quarter items so every wave does one w_in item plus a quarter (no second transpose round)
# speedup vs baseline: 1.0199x; 1.0032x over previous
.LBB0_102:
.LBB0_103:
	s_mulk_i32 s28, 0x2200
	v_and_b32_e32 v2, 56, v202
	s_add_i32 s2, s28, 0
	v_lshrrev_b32_e32 v13, 5, v208
	v_lshlrev_b32_e32 v10, 2, v12
	v_lshrrev_b32_e32 v14, 3, v208
	v_mul_u32_u24_e32 v8, 0x84, v2
	v_lshlrev_b32_e32 v2, 1, v2
	v_mov_b32_e32 v3, 0
	v_add_u32_e32 v18, s2, v10
	v_mul_u32_u24_e32 v19, 0x84, v13
	v_lshl_add_u64 v[6:7], s[82:83], 0, v[2:3]
	s_mov_b64 s[4:5], 0x900000
	v_lshlrev_b32_e32 v2, 2, v14
	v_lshl_add_u64 v[4:5], v[6:7], 0, s[4:5]
	v_add3_u32 v2, s2, v8, v2
	s_mov_b64 s[4:5], 0x100000
	v_mov_b32_e32 v11, v3
	s_lshl_b32 s2, s0, 1
	v_add_u32_e32 v25, v18, v19
	s_mov_b32 s3, 0
	v_or_b32_e32 v15, 8, v14
	v_or_b32_e32 v16, 16, v14
	v_or_b32_e32 v17, 24, v14
	v_lshl_add_u64 v[6:7], v[6:7], 0, s[4:5]
	v_lshl_add_u64 v[8:9], s[76:77], 0, v[10:11]
	v_lshl_add_u64 v[10:11], s[56:57], 0, v[10:11]
	s_lshl_b32 s7, s0, 5
	s_lshl_b32 s10, s1, 5
	s_add_i32 s11, s2, 0x1f000
	s_lshl_b32 s12, s1, 1
	s_movk_i32 s13, 0x7fff
	s_mov_b32 s14, 0xffff0000
	s_movk_i32 s15, 0x808
	s_movk_i32 s16, 0x4020
	v_add_u32_e32 v18, 0xc000, v25
	v_add_u32_e32 v19, 0xc400, v25
	v_add_u32_e32 v20, 0xc800, v25
	v_add_u32_e32 v21, 0xcc00, v25
	v_add_u32_e32 v22, 0xd000, v25
	v_add_u32_e32 v23, 0xd400, v25
	v_add_u32_e32 v24, 0xd800, v25
	v_add_u32_e32 v25, 0xdc00, v25
	v_add_u32_e32 v26, 0xc000, v2
	s_and_b32 s98, s0, 63
	s_lshl_b32 s98, s98, 4
	s_lshr_b32 s99, s0, 6
	s_lshl_b32 s99, s99, 5
	v_lshrrev_b32_e32 v108, 5, v208
	v_add_u32_e32 v108, s98, v108
	v_and_b32_e32 v109, 31, v208
	v_add_u32_e32 v109, s99, v109
	v_lshl_add_u32 v109, v108, 10, v109
	v_lshlrev_b32_e32 v109, 2, v109
	global_load_dword v100, v109, s[76:77] nt
	v_add_u32_e32 v108, 0x2000, v109
	global_load_dword v101, v108, s[76:77] nt
	v_add_u32_e32 v108, 0x4000, v109
	global_load_dword v102, v108, s[76:77] nt
	v_add_u32_e32 v108, 0x6000, v109
	global_load_dword v103, v108, s[76:77] nt
	v_add_u32_e32 v108, 0x8000, v109
	global_load_dword v104, v108, s[76:77] nt
	v_add_u32_e32 v108, 0xa000, v109
	global_load_dword v105, v108, s[76:77] nt
	v_add_u32_e32 v108, 0xc000, v109
	global_load_dword v106, v108, s[76:77] nt
	v_add_u32_e32 v108, 0xe000, v109
	global_load_dword v107, v108, s[76:77] nt
	v_lshrrev_b32_e32 v110, 5, v208
	v_mul_u32_u24_e32 v110, 0x84, v110
	v_and_b32_e32 v111, 31, v208
	v_lshl_add_u32 v110, v111, 2, v110
	s_add_i32 s100, s28, 0xc000
	v_add_u32_e32 v110, s100, v110
	v_and_b32_e32 v111, 1, v208
	v_mul_u32_u24_e32 v111, 0x420, v111
	v_lshrrev_b32_e32 v124, 1, v208
	v_lshl_add_u32 v111, v124, 2, v111
	v_add_u32_e32 v111, s100, v111
	v_add_u32_e32 v124, s99, v124
	v_lshlrev_b32_e32 v124, 11, v124
	v_and_b32_e32 v125, 1, v208
	v_lshl_add_u32 v125, v125, 3, s98
	v_lshl_add_u32 v124, v125, 1, v124
	s_branch .LBB0_107

.LBB0_106:
	s_add_i32 s0, s0, s1
	s_add_i32 s7, s7, s10
	s_add_i32 s11, s11, s12
	s_cmpk_gt_i32 s0, 0x7ff
	s_cbranch_scc1 .LBB0_115

.LBB0_115:
	s_waitcnt vmcnt(4)
	ds_write_b32 v110, v100
	ds_write_b32 v110, v101 offset:264
	ds_write_b32 v110, v102 offset:528
	ds_write_b32 v110, v103 offset:792
	ds_write_b32 v110, v104 offset:1056
	ds_write_b32 v110, v105 offset:1320
	ds_write_b32 v110, v106 offset:1584
	ds_write_b32 v110, v107 offset:1848
	s_waitcnt lgkmcnt(0)
	ds_read_b32 v112, v111
	ds_read_b32 v113, v111 offset:132
	ds_read_b32 v114, v111 offset:264
	ds_read_b32 v115, v111 offset:396
	ds_read_b32 v116, v111 offset:528
	ds_read_b32 v117, v111 offset:660
	ds_read_b32 v118, v111 offset:792
	ds_read_b32 v119, v111 offset:924
	s_waitcnt lgkmcnt(0)
	v_cvt_pk_bf16_f32 v120, v112, v113
	v_cvt_pk_bf16_f32 v121, v114, v115
	v_cvt_pk_bf16_f32 v122, v116, v117
	v_cvt_pk_bf16_f32 v123, v118, v119
	s_add_u32 s100, s82, 0x900000
	s_addc_u32 s101, s83, 0
	global_store_dwordx4 v124, v[120:123], s[100:101]
	v_mov_b32_e32 v2, v12
